# P1 norm epilogue: lane^16 / lane^32 exchanges via v_permlane16_swap / v_permlane32_swap instead of ds_bpermute LDS round trips (dead index math removed)
# speedup vs baseline: 1.0069x; 1.0069x over previous
;     __device__ __forceinline__ void operator()(f32x4 (&acc)[2][2][4][2], const Unit& u, int wr, int wc, int fr, int fq) const {
;     ...
;                 if (is_norm) {
;                     float ss = 0.f;
; #pragma unroll
;                     for (int bj = 0; bj < 2; ++bj)
; #pragma unroll
;                         for (int n = 0; n < 2; ++n) { const f32x4 x = v[bj][n]; ss += (x[0] * x[0] + x[1] * x[1]) + (x[2] * x[2] + x[3] * x[3]); }
;                     ss += __shfl_xor(ss, 16); ss += __shfl_xor(ss, 32);
;                     const float rs = rsqrtf(ss * (1.f / 64.f) + EPS);
; #pragma unroll
;                     for (int bj = 0; bj < 2; ++bj)
; #pragma unroll
;                         for (int n = 0; n < 2; ++n) v[bj][n] = v[bj][n] * rs * gv[bj][n];
.LBB0_153:
	s_and_b64 vcc, exec, s[0:1]
	s_cbranch_vccz .LBB0_155
	v_pk_mul_f32 v[146:147], v[144:145], v[144:145]
	v_pk_mul_f32 v[148:149], v[142:143], v[142:143]
	s_nop 0
	v_pk_mov_b32 v[150:151], v[148:149], v[146:147] op_sel:[1,0]
	v_mov_b32_e32 v149, v147
	v_pk_add_f32 v[146:147], v[150:151], v[148:149]
	v_pk_mul_f32 v[148:149], v[140:141], v[140:141]
	v_pk_mul_f32 v[150:151], v[138:139], v[138:139]
	v_pk_add_f32 v[146:147], v[146:147], v[146:147] op_sel:[0,1] op_sel_hi:[1,0]
	v_pk_mov_b32 v[152:153], v[150:151], v[148:149] op_sel:[1,0]
	v_mov_b32_e32 v151, v149
	v_pk_add_f32 v[148:149], v[152:153], v[150:151]
	v_mul_f32_e32 v150, v130, v130
	v_mul_f32_e32 v151, v131, v131
	v_pk_add_f32 v[148:149], v[148:149], v[148:149] op_sel:[0,1] op_sel_hi:[1,0]
	v_mov_b32_e32 v147, v150
	v_mov_b32_e32 v149, v151
	v_pk_add_f32 v[146:147], v[146:147], v[148:149]
	v_mul_f32_e32 v148, v135, v135
	v_mul_f32_e32 v150, v137, v137
	v_mul_f32_e32 v152, v132, v132
	v_mul_f32_e32 v153, v133, v133
	v_pk_fma_f32 v[148:149], v[134:135], v[134:135], v[148:149] op_sel_hi:[1,1,0]
	v_pk_fma_f32 v[150:151], v[136:137], v[136:137], v[150:151] op_sel_hi:[1,1,0]
	v_mov_b32_e32 v149, v152
	v_mov_b32_e32 v151, v153
	v_pk_add_f32 v[148:149], v[148:149], v[150:151]
	s_nop 0
	v_pk_add_f32 v[146:147], v[146:147], v[148:149]
	v_and_b32_e32 v148, 64, v196
	v_add_f32_e32 v146, v146, v147
	v_mov_b32_e32 v147, v146
	s_nop 1
	v_permlane16_swap_b32_e32 v147, v146
	s_waitcnt lgkmcnt(0)
	v_add_f32_e32 v146, v146, v147
	v_mov_b32_e32 v147, v146
	s_nop 1
	v_permlane32_swap_b32_e32 v147, v146
	s_waitcnt lgkmcnt(0)
	v_add_f32_e32 v146, v146, v147
	v_fmamk_f32 v146, v146, 0x3c800000, v195
	v_mul_f32_e32 v147, 0x4b800000, v146
	v_cmp_gt_f32_e32 vcc, s2, v146
	s_nop 1
	v_cndmask_b32_e32 v146, v146, v147, vcc
	v_rsq_f32_e32 v146, v146
	s_nop 0
	v_mul_f32_e32 v147, 0x45800000, v146
	v_cndmask_b32_e32 v158, v146, v147, vcc
	v_pk_mul_f32 v[142:143], v[142:143], v[158:159] op_sel_hi:[1,0]
	v_pk_mul_f32 v[144:145], v[144:145], v[158:159] op_sel_hi:[1,0]
	v_pk_mul_f32 v[138:139], v[138:139], v[158:159] op_sel_hi:[1,0]
	v_pk_mul_f32 v[140:141], v[140:141], v[158:159] op_sel_hi:[1,0]
	v_pk_mul_f32 v[134:135], v[134:135], v[158:159] op_sel_hi:[1,0]
	v_pk_mul_f32 v[136:137], v[136:137], v[158:159] op_sel_hi:[1,0]
	v_pk_mul_f32 v[130:131], v[130:131], v[158:159] op_sel_hi:[1,0]
	v_pk_mul_f32 v[132:133], v[132:133], v[158:159] op_sel_hi:[1,0]
	s_waitcnt vmcnt(0)
	v_pk_mul_f32 v[148:149], v[32:33], v[144:145]
	v_pk_mul_f32 v[146:147], v[30:31], v[142:143]
	v_pk_mul_f32 v[152:153], v[28:29], v[140:141]
	v_pk_mul_f32 v[150:151], v[26:27], v[138:139]
	v_pk_mul_f32 v[156:157], v[48:49], v[136:137]
	v_pk_mul_f32 v[154:155], v[46:47], v[134:135]
	v_pk_mul_f32 v[160:161], v[44:45], v[132:133]
	v_pk_mul_f32 v[158:159], v[42:43], v[130:131]

;     __device__ __forceinline__ void operator()(f32x4 (&acc)[2][2][4][2], const Unit& u, int wr, int wc, int fr, int fq) const {
;     ...
;                 if (is_norm) {
;                     float ss = 0.f;
; #pragma unroll
;                     for (int bj = 0; bj < 2; ++bj)
; #pragma unroll
;                         for (int n = 0; n < 2; ++n) { const f32x4 x = v[bj][n]; ss += (x[0] * x[0] + x[1] * x[1]) + (x[2] * x[2] + x[3] * x[3]); }
;                     ss += __shfl_xor(ss, 16); ss += __shfl_xor(ss, 32);
;                     const float rs = rsqrtf(ss * (1.f / 64.f) + EPS);
; #pragma unroll
;                     for (int bj = 0; bj < 2; ++bj)
; #pragma unroll
;                         for (int n = 0; n < 2; ++n) v[bj][n] = v[bj][n] * rs * gv[bj][n];
.LBB0_183:
	s_and_b64 vcc, exec, s[0:1]
	s_cbranch_vccz .LBB0_185
	v_pk_mul_f32 v[130:131], v[128:129], v[128:129]
	v_pk_mul_f32 v[132:133], v[126:127], v[126:127]
	s_nop 0
	v_pk_mov_b32 v[134:135], v[132:133], v[130:131] op_sel:[1,0]
	v_mov_b32_e32 v133, v131
	v_pk_add_f32 v[130:131], v[134:135], v[132:133]
	v_pk_mul_f32 v[132:133], v[124:125], v[124:125]
	v_pk_mul_f32 v[134:135], v[122:123], v[122:123]
	v_pk_add_f32 v[130:131], v[130:131], v[130:131] op_sel:[0,1] op_sel_hi:[1,0]
	v_pk_mov_b32 v[136:137], v[134:135], v[132:133] op_sel:[1,0]
	v_mov_b32_e32 v135, v133
	v_pk_add_f32 v[132:133], v[136:137], v[134:135]
	v_mul_f32_e32 v134, v114, v114
	v_mul_f32_e32 v135, v115, v115
	v_pk_add_f32 v[132:133], v[132:133], v[132:133] op_sel:[0,1] op_sel_hi:[1,0]
	v_mov_b32_e32 v131, v134
	v_mov_b32_e32 v133, v135
	v_pk_add_f32 v[130:131], v[130:131], v[132:133]
	v_mul_f32_e32 v132, v119, v119
	v_mul_f32_e32 v134, v121, v121
	v_mul_f32_e32 v136, v116, v116
	v_mul_f32_e32 v137, v117, v117
	v_pk_fma_f32 v[132:133], v[118:119], v[118:119], v[132:133] op_sel_hi:[1,1,0]
	v_pk_fma_f32 v[134:135], v[120:121], v[120:121], v[134:135] op_sel_hi:[1,1,0]
	v_mov_b32_e32 v133, v136
	v_mov_b32_e32 v135, v137
	v_pk_add_f32 v[132:133], v[132:133], v[134:135]
	s_nop 0
	v_pk_add_f32 v[130:131], v[130:131], v[132:133]
	v_and_b32_e32 v132, 64, v196
	v_add_f32_e32 v130, v130, v131
	v_mov_b32_e32 v131, v130
	s_nop 1
	v_permlane16_swap_b32_e32 v131, v130
	s_waitcnt lgkmcnt(0)
	v_add_f32_e32 v130, v130, v131
	v_mov_b32_e32 v131, v130
	s_nop 1
	v_permlane32_swap_b32_e32 v131, v130
	s_waitcnt lgkmcnt(0)
	v_add_f32_e32 v130, v130, v131
	v_fmamk_f32 v130, v130, 0x3c800000, v195
	v_mul_f32_e32 v131, 0x4b800000, v130
	v_cmp_gt_f32_e32 vcc, s2, v130
	s_nop 1
	v_cndmask_b32_e32 v130, v130, v131, vcc
	v_rsq_f32_e32 v130, v130
	s_nop 0
	v_mul_f32_e32 v131, 0x45800000, v130
	v_cndmask_b32_e32 v142, v130, v131, vcc
	v_pk_mul_f32 v[126:127], v[126:127], v[142:143] op_sel_hi:[1,0]
	v_pk_mul_f32 v[128:129], v[128:129], v[142:143] op_sel_hi:[1,0]
	v_pk_mul_f32 v[122:123], v[122:123], v[142:143] op_sel_hi:[1,0]
	v_pk_mul_f32 v[124:125], v[124:125], v[142:143] op_sel_hi:[1,0]
	v_pk_mul_f32 v[118:119], v[118:119], v[142:143] op_sel_hi:[1,0]
	v_pk_mul_f32 v[120:121], v[120:121], v[142:143] op_sel_hi:[1,0]
	v_pk_mul_f32 v[114:115], v[114:115], v[142:143] op_sel_hi:[1,0]
	v_pk_mul_f32 v[116:117], v[116:117], v[142:143] op_sel_hi:[1,0]
	v_pk_mul_f32 v[132:133], v[32:33], v[128:129]
	v_pk_mul_f32 v[130:131], v[30:31], v[126:127]
	v_pk_mul_f32 v[136:137], v[28:29], v[124:125]
	v_pk_mul_f32 v[134:135], v[26:27], v[122:123]
	v_pk_mul_f32 v[140:141], v[48:49], v[120:121]
	v_pk_mul_f32 v[138:139], v[46:47], v[118:119]
	v_pk_mul_f32 v[144:145], v[44:45], v[116:117]
	v_pk_mul_f32 v[142:143], v[42:43], v[114:115]

;     __device__ __forceinline__ void operator()(f32x4 (&acc)[2][2][4][2], const Unit& u, int wr, int wc, int fr, int fq) const {
;     ...
;                 if (is_norm) {
;                     float ss = 0.f;
; #pragma unroll
;                     for (int bj = 0; bj < 2; ++bj)
; #pragma unroll
;                         for (int n = 0; n < 2; ++n) { const f32x4 x = v[bj][n]; ss += (x[0] * x[0] + x[1] * x[1]) + (x[2] * x[2] + x[3] * x[3]); }
;                     ss += __shfl_xor(ss, 16); ss += __shfl_xor(ss, 32);
;                     const float rs = rsqrtf(ss * (1.f / 64.f) + EPS);
; #pragma unroll
;                     for (int bj = 0; bj < 2; ++bj)
; #pragma unroll
;                         for (int n = 0; n < 2; ++n) v[bj][n] = v[bj][n] * rs * gv[bj][n];
.LBB0_198:
	s_and_b64 vcc, exec, s[0:1]
	s_cbranch_vccz .LBB0_215
	v_pk_mul_f32 v[114:115], v[112:113], v[112:113]
	v_pk_mul_f32 v[116:117], v[110:111], v[110:111]
	s_nop 0
	v_pk_mov_b32 v[118:119], v[116:117], v[114:115] op_sel:[1,0]
	v_mov_b32_e32 v117, v115
	v_pk_add_f32 v[114:115], v[118:119], v[116:117]
	v_pk_mul_f32 v[116:117], v[108:109], v[108:109]
	v_pk_mul_f32 v[118:119], v[106:107], v[106:107]
	v_pk_add_f32 v[114:115], v[114:115], v[114:115] op_sel:[0,1] op_sel_hi:[1,0]
	v_pk_mov_b32 v[120:121], v[118:119], v[116:117] op_sel:[1,0]
	v_mov_b32_e32 v119, v117
	v_pk_add_f32 v[116:117], v[120:121], v[118:119]
	v_mul_f32_e32 v118, v98, v98
	v_mul_f32_e32 v119, v99, v99
	v_pk_add_f32 v[116:117], v[116:117], v[116:117] op_sel:[0,1] op_sel_hi:[1,0]
	v_mov_b32_e32 v115, v118
	v_mov_b32_e32 v117, v119
	v_pk_add_f32 v[114:115], v[114:115], v[116:117]
	v_mul_f32_e32 v116, v103, v103
	v_mul_f32_e32 v118, v105, v105
	v_mul_f32_e32 v120, v100, v100
	v_mul_f32_e32 v121, v101, v101
	v_pk_fma_f32 v[116:117], v[102:103], v[102:103], v[116:117] op_sel_hi:[1,1,0]
	v_pk_fma_f32 v[118:119], v[104:105], v[104:105], v[118:119] op_sel_hi:[1,1,0]
	v_mov_b32_e32 v117, v120
	v_mov_b32_e32 v119, v121
	v_pk_add_f32 v[116:117], v[116:117], v[118:119]
	s_nop 0
	v_pk_add_f32 v[114:115], v[114:115], v[116:117]
	v_and_b32_e32 v116, 64, v196
	v_add_f32_e32 v114, v114, v115
	v_mov_b32_e32 v115, v114
	s_nop 1
	v_permlane16_swap_b32_e32 v115, v114
	s_waitcnt lgkmcnt(0)
	v_add_f32_e32 v114, v114, v115
	v_mov_b32_e32 v115, v114
	s_nop 1
	v_permlane32_swap_b32_e32 v115, v114
	s_waitcnt lgkmcnt(0)
	v_add_f32_e32 v114, v114, v115
	v_fmamk_f32 v114, v114, 0x3c800000, v195
	v_mul_f32_e32 v115, 0x4b800000, v114
	v_cmp_gt_f32_e32 vcc, s2, v114
	s_nop 1
	v_cndmask_b32_e32 v114, v114, v115, vcc
	v_rsq_f32_e32 v114, v114
	s_nop 0
	v_mul_f32_e32 v115, 0x45800000, v114
	v_cndmask_b32_e32 v126, v114, v115, vcc
	v_pk_mul_f32 v[110:111], v[110:111], v[126:127] op_sel_hi:[1,0]
	v_pk_mul_f32 v[112:113], v[112:113], v[126:127] op_sel_hi:[1,0]
	v_pk_mul_f32 v[106:107], v[106:107], v[126:127] op_sel_hi:[1,0]
	v_pk_mul_f32 v[108:109], v[108:109], v[126:127] op_sel_hi:[1,0]
	v_pk_mul_f32 v[102:103], v[102:103], v[126:127] op_sel_hi:[1,0]
	v_pk_mul_f32 v[104:105], v[104:105], v[126:127] op_sel_hi:[1,0]
	v_pk_mul_f32 v[98:99], v[98:99], v[126:127] op_sel_hi:[1,0]
	v_pk_mul_f32 v[100:101], v[100:101], v[126:127] op_sel_hi:[1,0]
	v_pk_mul_f32 v[116:117], v[32:33], v[112:113]
	v_pk_mul_f32 v[114:115], v[30:31], v[110:111]
	v_pk_mul_f32 v[120:121], v[28:29], v[108:109]
	v_pk_mul_f32 v[118:119], v[26:27], v[106:107]
	v_pk_mul_f32 v[124:125], v[48:49], v[104:105]
	v_pk_mul_f32 v[122:123], v[46:47], v[102:103]
	v_pk_mul_f32 v[128:129], v[44:45], v[100:101]
	v_pk_mul_f32 v[126:127], v[42:43], v[98:99]
	s_and_b64 vcc, exec, s[8:9]
	v_or_b32_e32 v100, s27, v190
	s_cbranch_vccnz .LBB0_225
	s_branch .LBB0_216

;     __device__ __forceinline__ void operator()(f32x4 (&acc)[2][2][4][2], const Unit& u, int wr, int wc, int fr, int fq) const {
;     ...
;                 if (is_norm) {
;                     float ss = 0.f;
; #pragma unroll
;                     for (int bj = 0; bj < 2; ++bj)
; #pragma unroll
;                         for (int n = 0; n < 2; ++n) { const f32x4 x = v[bj][n]; ss += (x[0] * x[0] + x[1] * x[1]) + (x[2] * x[2] + x[3] * x[3]); }
;                     ss += __shfl_xor(ss, 16); ss += __shfl_xor(ss, 32);
;                     const float rs = rsqrtf(ss * (1.f / 64.f) + EPS);
; #pragma unroll
;                     for (int bj = 0; bj < 2; ++bj)
; #pragma unroll
;                         for (int n = 0; n < 2; ++n) v[bj][n] = v[bj][n] * rs * gv[bj][n];
.LBB0_228:
	s_and_b64 vcc, exec, s[0:1]
	s_cbranch_vccz .LBB0_245
	v_pk_mul_f32 v[98:99], v[96:97], v[96:97]
	v_pk_mul_f32 v[100:101], v[94:95], v[94:95]
	s_nop 0
	v_pk_mov_b32 v[102:103], v[100:101], v[98:99] op_sel:[1,0]
	v_mov_b32_e32 v101, v99
	v_pk_add_f32 v[98:99], v[102:103], v[100:101]
	v_pk_mul_f32 v[100:101], v[92:93], v[92:93]
	v_pk_mul_f32 v[102:103], v[90:91], v[90:91]
	v_pk_add_f32 v[98:99], v[98:99], v[98:99] op_sel:[0,1] op_sel_hi:[1,0]
	v_pk_mov_b32 v[104:105], v[102:103], v[100:101] op_sel:[1,0]
	v_mov_b32_e32 v103, v101
	v_pk_add_f32 v[100:101], v[104:105], v[102:103]
	v_mul_f32_e32 v102, v82, v82
	v_mul_f32_e32 v103, v83, v83
	v_pk_add_f32 v[100:101], v[100:101], v[100:101] op_sel:[0,1] op_sel_hi:[1,0]
	v_mov_b32_e32 v99, v102
	v_mov_b32_e32 v101, v103
	v_pk_add_f32 v[98:99], v[98:99], v[100:101]
	v_mul_f32_e32 v100, v87, v87
	v_mul_f32_e32 v102, v89, v89
	v_mul_f32_e32 v104, v84, v84
	v_mul_f32_e32 v105, v85, v85
	v_pk_fma_f32 v[100:101], v[86:87], v[86:87], v[100:101] op_sel_hi:[1,1,0]
	v_pk_fma_f32 v[102:103], v[88:89], v[88:89], v[102:103] op_sel_hi:[1,1,0]
	v_mov_b32_e32 v101, v104
	v_mov_b32_e32 v103, v105
	v_pk_add_f32 v[100:101], v[100:101], v[102:103]
	s_nop 0
	v_pk_add_f32 v[98:99], v[98:99], v[100:101]
	v_and_b32_e32 v100, 64, v196
	v_add_f32_e32 v98, v98, v99
	v_mov_b32_e32 v99, v98
	s_nop 1
	v_permlane16_swap_b32_e32 v99, v98
	s_waitcnt lgkmcnt(0)
	v_add_f32_e32 v98, v98, v99
	v_mov_b32_e32 v99, v98
	s_nop 1
	v_permlane32_swap_b32_e32 v99, v98
	s_waitcnt lgkmcnt(0)
	v_add_f32_e32 v98, v98, v99
	v_fmamk_f32 v98, v98, 0x3c800000, v195
	v_mul_f32_e32 v99, 0x4b800000, v98
	v_cmp_gt_f32_e32 vcc, s2, v98
	s_nop 1
	v_cndmask_b32_e32 v98, v98, v99, vcc
	v_rsq_f32_e32 v98, v98
	s_nop 0
	v_mul_f32_e32 v99, 0x45800000, v98
	v_cndmask_b32_e32 v110, v98, v99, vcc
	v_pk_mul_f32 v[94:95], v[94:95], v[110:111] op_sel_hi:[1,0]
	v_pk_mul_f32 v[96:97], v[96:97], v[110:111] op_sel_hi:[1,0]
	v_pk_mul_f32 v[90:91], v[90:91], v[110:111] op_sel_hi:[1,0]
	v_pk_mul_f32 v[92:93], v[92:93], v[110:111] op_sel_hi:[1,0]
	v_pk_mul_f32 v[86:87], v[86:87], v[110:111] op_sel_hi:[1,0]
	v_pk_mul_f32 v[88:89], v[88:89], v[110:111] op_sel_hi:[1,0]
	v_pk_mul_f32 v[82:83], v[82:83], v[110:111] op_sel_hi:[1,0]
	v_pk_mul_f32 v[84:85], v[84:85], v[110:111] op_sel_hi:[1,0]
	v_pk_mul_f32 v[100:101], v[32:33], v[96:97]
	v_pk_mul_f32 v[98:99], v[30:31], v[94:95]
	v_pk_mul_f32 v[104:105], v[28:29], v[92:93]
	v_pk_mul_f32 v[102:103], v[26:27], v[90:91]
	v_pk_mul_f32 v[108:109], v[48:49], v[88:89]
	v_pk_mul_f32 v[106:107], v[46:47], v[86:87]
	v_pk_mul_f32 v[112:113], v[44:45], v[84:85]
	v_pk_mul_f32 v[110:111], v[42:43], v[82:83]
	s_and_b64 vcc, exec, s[8:9]
	v_or_b32_e32 v84, s27, v191
	s_cbranch_vccnz .LBB0_255
	s_branch .LBB0_246

;     __device__ __forceinline__ void operator()(f32x4 (&acc)[2][2][4][2], const Unit& u, int wr, int wc, int fr, int fq) const {
;     ...
;                 if (is_norm) {
;                     float ss = 0.f;
; #pragma unroll
;                     for (int bj = 0; bj < 2; ++bj)
; #pragma unroll
;                         for (int n = 0; n < 2; ++n) { const f32x4 x = v[bj][n]; ss += (x[0] * x[0] + x[1] * x[1]) + (x[2] * x[2] + x[3] * x[3]); }
;                     ss += __shfl_xor(ss, 16); ss += __shfl_xor(ss, 32);
;                     const float rs = rsqrtf(ss * (1.f / 64.f) + EPS);
; #pragma unroll
;                     for (int bj = 0; bj < 2; ++bj)
; #pragma unroll
;                         for (int n = 0; n < 2; ++n) v[bj][n] = v[bj][n] * rs * gv[bj][n];
.LBB0_273:
	s_and_b64 vcc, exec, s[0:1]
	s_cbranch_vccz .LBB0_275
	v_pk_mul_f32 v[82:83], v[80:81], v[80:81]
	v_pk_mul_f32 v[84:85], v[78:79], v[78:79]
	s_nop 0
	v_pk_mov_b32 v[86:87], v[84:85], v[82:83] op_sel:[1,0]
	v_mov_b32_e32 v85, v83
	v_pk_add_f32 v[82:83], v[86:87], v[84:85]
	v_pk_mul_f32 v[84:85], v[76:77], v[76:77]
	v_pk_mul_f32 v[86:87], v[74:75], v[74:75]
	v_pk_add_f32 v[82:83], v[82:83], v[82:83] op_sel:[0,1] op_sel_hi:[1,0]
	v_pk_mov_b32 v[88:89], v[86:87], v[84:85] op_sel:[1,0]
	v_mov_b32_e32 v87, v85
	v_pk_add_f32 v[84:85], v[88:89], v[86:87]
	v_mul_f32_e32 v86, v66, v66
	v_mul_f32_e32 v87, v67, v67
	v_pk_add_f32 v[84:85], v[84:85], v[84:85] op_sel:[0,1] op_sel_hi:[1,0]
	v_mov_b32_e32 v83, v86
	v_mov_b32_e32 v85, v87
	v_pk_add_f32 v[82:83], v[82:83], v[84:85]
	v_mul_f32_e32 v84, v71, v71
	v_mul_f32_e32 v86, v73, v73
	v_mul_f32_e32 v88, v68, v68
	v_mul_f32_e32 v89, v69, v69
	v_pk_fma_f32 v[84:85], v[70:71], v[70:71], v[84:85] op_sel_hi:[1,1,0]
	v_pk_fma_f32 v[86:87], v[72:73], v[72:73], v[86:87] op_sel_hi:[1,1,0]
	v_mov_b32_e32 v85, v88
	v_mov_b32_e32 v87, v89
	v_pk_add_f32 v[84:85], v[84:85], v[86:87]
	s_nop 0
	v_pk_add_f32 v[82:83], v[82:83], v[84:85]
	v_and_b32_e32 v84, 64, v196
	v_add_f32_e32 v82, v82, v83
	v_mov_b32_e32 v83, v82
	s_nop 1
	v_permlane16_swap_b32_e32 v83, v82
	s_waitcnt lgkmcnt(0)
	v_add_f32_e32 v82, v82, v83
	v_mov_b32_e32 v83, v82
	s_nop 1
	v_permlane32_swap_b32_e32 v83, v82
	s_waitcnt lgkmcnt(0)
	v_add_f32_e32 v82, v82, v83
	v_fmamk_f32 v82, v82, 0x3c800000, v195
	v_mul_f32_e32 v83, 0x4b800000, v82
	v_cmp_gt_f32_e32 vcc, s2, v82
	s_nop 1
	v_cndmask_b32_e32 v82, v82, v83, vcc
	v_rsq_f32_e32 v82, v82
	s_nop 0
	v_mul_f32_e32 v83, 0x45800000, v82
	v_cndmask_b32_e32 v94, v82, v83, vcc
	v_pk_mul_f32 v[78:79], v[78:79], v[94:95] op_sel_hi:[1,0]
	v_pk_mul_f32 v[80:81], v[80:81], v[94:95] op_sel_hi:[1,0]
	v_pk_mul_f32 v[74:75], v[74:75], v[94:95] op_sel_hi:[1,0]
	v_pk_mul_f32 v[76:77], v[76:77], v[94:95] op_sel_hi:[1,0]
	v_pk_mul_f32 v[70:71], v[70:71], v[94:95] op_sel_hi:[1,0]
	v_pk_mul_f32 v[72:73], v[72:73], v[94:95] op_sel_hi:[1,0]
	v_pk_mul_f32 v[66:67], v[66:67], v[94:95] op_sel_hi:[1,0]
	v_pk_mul_f32 v[68:69], v[68:69], v[94:95] op_sel_hi:[1,0]
	v_pk_mul_f32 v[84:85], v[32:33], v[80:81]
	v_pk_mul_f32 v[82:83], v[30:31], v[78:79]
	v_pk_mul_f32 v[88:89], v[28:29], v[76:77]
	v_pk_mul_f32 v[86:87], v[26:27], v[74:75]
	v_pk_mul_f32 v[92:93], v[48:49], v[72:73]
	v_pk_mul_f32 v[90:91], v[46:47], v[70:71]
	v_pk_mul_f32 v[96:97], v[44:45], v[68:69]
	v_pk_mul_f32 v[94:95], v[42:43], v[66:67]

;     __device__ __forceinline__ void operator()(f32x4 (&acc)[2][2][4][2], const Unit& u, int wr, int wc, int fr, int fq) const {
;     ...
;                 if (is_norm) {
;                     float ss = 0.f;
; #pragma unroll
;                     for (int bj = 0; bj < 2; ++bj)
; #pragma unroll
;                         for (int n = 0; n < 2; ++n) { const f32x4 x = v[bj][n]; ss += (x[0] * x[0] + x[1] * x[1]) + (x[2] * x[2] + x[3] * x[3]); }
;                     ss += __shfl_xor(ss, 16); ss += __shfl_xor(ss, 32);
;                     const float rs = rsqrtf(ss * (1.f / 64.f) + EPS);
; #pragma unroll
;                     for (int bj = 0; bj < 2; ++bj)
; #pragma unroll
;                         for (int n = 0; n < 2; ++n) v[bj][n] = v[bj][n] * rs * gv[bj][n];
.LBB0_288:
	s_and_b64 vcc, exec, s[0:1]
	s_cbranch_vccz .LBB0_305
	v_pk_mul_f32 v[66:67], v[64:65], v[64:65]
	v_pk_mul_f32 v[68:69], v[62:63], v[62:63]
	s_nop 0
	v_pk_mov_b32 v[70:71], v[68:69], v[66:67] op_sel:[1,0]
	v_mov_b32_e32 v69, v67
	v_pk_add_f32 v[66:67], v[70:71], v[68:69]
	v_pk_mul_f32 v[68:69], v[60:61], v[60:61]
	v_pk_mul_f32 v[70:71], v[58:59], v[58:59]
	v_pk_add_f32 v[66:67], v[66:67], v[66:67] op_sel:[0,1] op_sel_hi:[1,0]
	v_pk_mov_b32 v[72:73], v[70:71], v[68:69] op_sel:[1,0]
	v_mov_b32_e32 v71, v69
	v_pk_add_f32 v[68:69], v[72:73], v[70:71]
	v_mul_f32_e32 v70, v50, v50
	v_mul_f32_e32 v71, v51, v51
	v_pk_add_f32 v[68:69], v[68:69], v[68:69] op_sel:[0,1] op_sel_hi:[1,0]
	v_mov_b32_e32 v67, v70
	v_mov_b32_e32 v69, v71
	v_pk_add_f32 v[66:67], v[66:67], v[68:69]
	v_mul_f32_e32 v68, v55, v55
	v_mul_f32_e32 v70, v57, v57
	v_mul_f32_e32 v72, v52, v52
	v_mul_f32_e32 v73, v53, v53
	v_pk_fma_f32 v[68:69], v[54:55], v[54:55], v[68:69] op_sel_hi:[1,1,0]
	v_pk_fma_f32 v[70:71], v[56:57], v[56:57], v[70:71] op_sel_hi:[1,1,0]
	v_mov_b32_e32 v69, v72
	v_mov_b32_e32 v71, v73
	v_pk_add_f32 v[68:69], v[68:69], v[70:71]
	s_nop 0
	v_pk_add_f32 v[66:67], v[66:67], v[68:69]
	v_and_b32_e32 v68, 64, v196
	v_add_f32_e32 v66, v66, v67
	v_mov_b32_e32 v67, v66
	s_nop 1
	v_permlane16_swap_b32_e32 v67, v66
	s_waitcnt lgkmcnt(0)
	v_add_f32_e32 v66, v66, v67
	v_mov_b32_e32 v67, v66
	s_nop 1
	v_permlane32_swap_b32_e32 v67, v66
	s_waitcnt lgkmcnt(0)
	v_add_f32_e32 v66, v66, v67
	v_fmamk_f32 v66, v66, 0x3c800000, v195
	v_mul_f32_e32 v67, 0x4b800000, v66
	v_cmp_gt_f32_e32 vcc, s2, v66
	s_nop 1
	v_cndmask_b32_e32 v66, v66, v67, vcc
	v_rsq_f32_e32 v66, v66
	s_nop 0
	v_mul_f32_e32 v67, 0x45800000, v66
	v_cndmask_b32_e32 v78, v66, v67, vcc
	v_pk_mul_f32 v[62:63], v[62:63], v[78:79] op_sel_hi:[1,0]
	v_pk_mul_f32 v[64:65], v[64:65], v[78:79] op_sel_hi:[1,0]
	v_pk_mul_f32 v[58:59], v[58:59], v[78:79] op_sel_hi:[1,0]
	v_pk_mul_f32 v[60:61], v[60:61], v[78:79] op_sel_hi:[1,0]
	v_pk_mul_f32 v[54:55], v[54:55], v[78:79] op_sel_hi:[1,0]
	v_pk_mul_f32 v[56:57], v[56:57], v[78:79] op_sel_hi:[1,0]
	v_pk_mul_f32 v[50:51], v[50:51], v[78:79] op_sel_hi:[1,0]
	v_pk_mul_f32 v[52:53], v[52:53], v[78:79] op_sel_hi:[1,0]
	v_pk_mul_f32 v[68:69], v[32:33], v[64:65]
	v_pk_mul_f32 v[66:67], v[30:31], v[62:63]
	v_pk_mul_f32 v[72:73], v[28:29], v[60:61]
	v_pk_mul_f32 v[70:71], v[26:27], v[58:59]
	v_pk_mul_f32 v[76:77], v[48:49], v[56:57]
	v_pk_mul_f32 v[74:75], v[46:47], v[54:55]
	v_pk_mul_f32 v[80:81], v[44:45], v[52:53]
	v_pk_mul_f32 v[78:79], v[42:43], v[50:51]
	s_and_b64 vcc, exec, s[8:9]
	v_or_b32_e32 v52, s33, v189
	s_cbranch_vccnz .LBB0_315
	s_branch .LBB0_306

;     __device__ __forceinline__ void operator()(f32x4 (&acc)[2][2][4][2], const Unit& u, int wr, int wc, int fr, int fq) const {
;     ...
;                 if (is_norm) {
;                     float ss = 0.f;
; #pragma unroll
;                     for (int bj = 0; bj < 2; ++bj)
; #pragma unroll
;                         for (int n = 0; n < 2; ++n) { const f32x4 x = v[bj][n]; ss += (x[0] * x[0] + x[1] * x[1]) + (x[2] * x[2] + x[3] * x[3]); }
;                     ss += __shfl_xor(ss, 16); ss += __shfl_xor(ss, 32);
;                     const float rs = rsqrtf(ss * (1.f / 64.f) + EPS);
; #pragma unroll
;                     for (int bj = 0; bj < 2; ++bj)
; #pragma unroll
;                         for (int n = 0; n < 2; ++n) v[bj][n] = v[bj][n] * rs * gv[bj][n];
.LBB0_318:
	s_and_b64 vcc, exec, s[0:1]
	s_cbranch_vccz .LBB0_335
	v_pk_mul_f32 v[50:51], v[40:41], v[40:41]
	v_pk_mul_f32 v[52:53], v[38:39], v[38:39]
	s_nop 0
	v_pk_mov_b32 v[54:55], v[52:53], v[50:51] op_sel:[1,0]
	v_mov_b32_e32 v53, v51
	v_pk_add_f32 v[50:51], v[54:55], v[52:53]
	v_pk_mul_f32 v[52:53], v[36:37], v[36:37]
	v_pk_mul_f32 v[54:55], v[34:35], v[34:35]
	v_pk_add_f32 v[50:51], v[50:51], v[50:51] op_sel:[0,1] op_sel_hi:[1,0]
	v_pk_mov_b32 v[56:57], v[54:55], v[52:53] op_sel:[1,0]
	v_mov_b32_e32 v55, v53
	v_pk_add_f32 v[52:53], v[56:57], v[54:55]
	v_mul_f32_e32 v54, v18, v18
	v_mul_f32_e32 v55, v19, v19
	v_pk_add_f32 v[52:53], v[52:53], v[52:53] op_sel:[0,1] op_sel_hi:[1,0]
	v_mov_b32_e32 v51, v54
	v_mov_b32_e32 v53, v55
	v_pk_add_f32 v[50:51], v[50:51], v[52:53]
	v_mul_f32_e32 v52, v23, v23
	v_mul_f32_e32 v54, v25, v25
	v_mul_f32_e32 v56, v20, v20
	v_mul_f32_e32 v57, v21, v21
	v_pk_fma_f32 v[52:53], v[22:23], v[22:23], v[52:53] op_sel_hi:[1,1,0]
	v_pk_fma_f32 v[54:55], v[24:25], v[24:25], v[54:55] op_sel_hi:[1,1,0]
	v_mov_b32_e32 v53, v56
	v_mov_b32_e32 v55, v57
	v_pk_add_f32 v[52:53], v[52:53], v[54:55]
	s_nop 0
	v_pk_add_f32 v[50:51], v[50:51], v[52:53]
	v_and_b32_e32 v52, 64, v196
	v_add_f32_e32 v50, v50, v51
	v_mov_b32_e32 v51, v50
	s_nop 1
	v_permlane16_swap_b32_e32 v51, v50
	s_waitcnt lgkmcnt(0)
	v_add_f32_e32 v50, v50, v51
	v_mov_b32_e32 v51, v50
	s_nop 1
	v_permlane32_swap_b32_e32 v51, v50
	s_waitcnt lgkmcnt(0)
	v_add_f32_e32 v50, v50, v51
	v_fmamk_f32 v50, v50, 0x3c800000, v195
	v_mul_f32_e32 v51, 0x4b800000, v50
	v_cmp_gt_f32_e32 vcc, s2, v50
	s_nop 1
	v_cndmask_b32_e32 v50, v50, v51, vcc
	v_rsq_f32_e32 v50, v50
	s_nop 0
	v_mul_f32_e32 v51, 0x45800000, v50
	v_cndmask_b32_e32 v62, v50, v51, vcc
	v_pk_mul_f32 v[38:39], v[38:39], v[62:63] op_sel_hi:[1,0]
	v_pk_mul_f32 v[40:41], v[40:41], v[62:63] op_sel_hi:[1,0]
	v_pk_mul_f32 v[34:35], v[34:35], v[62:63] op_sel_hi:[1,0]
	v_pk_mul_f32 v[36:37], v[36:37], v[62:63] op_sel_hi:[1,0]
	v_pk_mul_f32 v[22:23], v[22:23], v[62:63] op_sel_hi:[1,0]
	v_pk_mul_f32 v[24:25], v[24:25], v[62:63] op_sel_hi:[1,0]
	v_pk_mul_f32 v[18:19], v[18:19], v[62:63] op_sel_hi:[1,0]
	v_pk_mul_f32 v[20:21], v[20:21], v[62:63] op_sel_hi:[1,0]
	v_pk_mul_f32 v[52:53], v[32:33], v[40:41]
	v_pk_mul_f32 v[50:51], v[30:31], v[38:39]
	v_pk_mul_f32 v[56:57], v[28:29], v[36:37]
	v_pk_mul_f32 v[54:55], v[26:27], v[34:35]
	v_pk_mul_f32 v[60:61], v[48:49], v[24:25]
	v_pk_mul_f32 v[58:59], v[46:47], v[22:23]
	v_pk_mul_f32 v[64:65], v[44:45], v[20:21]
	v_pk_mul_f32 v[62:63], v[42:43], v[18:19]
	s_and_b64 vcc, exec, s[8:9]
	v_or_b32_e32 v20, s33, v190
	s_cbranch_vccnz .LBB0_345
	s_branch .LBB0_336

;     __device__ __forceinline__ void operator()(f32x4 (&acc)[2][2][4][2], const Unit& u, int wr, int wc, int fr, int fq) const {
;     ...
;                 if (is_norm) {
;                     float ss = 0.f;
; #pragma unroll
;                     for (int bj = 0; bj < 2; ++bj)
; #pragma unroll
;                         for (int n = 0; n < 2; ++n) { const f32x4 x = v[bj][n]; ss += (x[0] * x[0] + x[1] * x[1]) + (x[2] * x[2] + x[3] * x[3]); }
;                     ss += __shfl_xor(ss, 16); ss += __shfl_xor(ss, 32);
;                     const float rs = rsqrtf(ss * (1.f / 64.f) + EPS);
; #pragma unroll
;                     for (int bj = 0; bj < 2; ++bj)
; #pragma unroll
;                         for (int n = 0; n < 2; ++n) v[bj][n] = v[bj][n] * rs * gv[bj][n];
.LBB0_348:
	s_and_b64 vcc, exec, s[0:1]
	s_cbranch_vccz .LBB0_365
	v_pk_mul_f32 v[18:19], v[16:17], v[16:17]
	v_pk_mul_f32 v[20:21], v[14:15], v[14:15]
	s_nop 0
	v_pk_mov_b32 v[22:23], v[20:21], v[18:19] op_sel:[1,0]
	v_mov_b32_e32 v21, v19
	v_pk_add_f32 v[18:19], v[22:23], v[20:21]
	v_pk_mul_f32 v[20:21], v[12:13], v[12:13]
	v_pk_mul_f32 v[22:23], v[10:11], v[10:11]
	v_pk_add_f32 v[18:19], v[18:19], v[18:19] op_sel:[0,1] op_sel_hi:[1,0]
	v_pk_mov_b32 v[24:25], v[22:23], v[20:21] op_sel:[1,0]
	v_mov_b32_e32 v23, v21
	v_pk_add_f32 v[20:21], v[24:25], v[22:23]
	v_mul_f32_e32 v22, v2, v2
	v_mul_f32_e32 v23, v3, v3
	v_pk_add_f32 v[20:21], v[20:21], v[20:21] op_sel:[0,1] op_sel_hi:[1,0]
	v_mov_b32_e32 v19, v22
	v_mov_b32_e32 v21, v23
	v_pk_add_f32 v[18:19], v[18:19], v[20:21]
	v_mul_f32_e32 v20, v7, v7
	v_mul_f32_e32 v22, v9, v9
	v_mul_f32_e32 v24, v4, v4
	v_mul_f32_e32 v25, v5, v5
	v_pk_fma_f32 v[20:21], v[6:7], v[6:7], v[20:21] op_sel_hi:[1,1,0]
	v_pk_fma_f32 v[22:23], v[8:9], v[8:9], v[22:23] op_sel_hi:[1,1,0]
	v_mov_b32_e32 v21, v24
	v_mov_b32_e32 v23, v25
	v_pk_add_f32 v[20:21], v[20:21], v[22:23]
	s_nop 0
	v_pk_add_f32 v[18:19], v[18:19], v[20:21]
	v_and_b32_e32 v20, 64, v196
	v_add_f32_e32 v18, v18, v19
	v_mov_b32_e32 v19, v18
	s_nop 1
	v_permlane16_swap_b32_e32 v19, v18
	s_waitcnt lgkmcnt(0)
	v_add_f32_e32 v18, v18, v19
	v_mov_b32_e32 v19, v18
	s_nop 1
	v_permlane32_swap_b32_e32 v19, v18
	s_waitcnt lgkmcnt(0)
	v_add_f32_e32 v18, v18, v19
	v_fmamk_f32 v18, v18, 0x3c800000, v195
	v_mul_f32_e32 v19, 0x4b800000, v18
	v_cmp_gt_f32_e32 vcc, s2, v18
	s_nop 1
	v_cndmask_b32_e32 v18, v18, v19, vcc
	v_rsq_f32_e32 v18, v18
	s_nop 0
	v_mul_f32_e32 v19, 0x45800000, v18
	v_cndmask_b32_e32 v38, v18, v19, vcc
	v_pk_mul_f32 v[14:15], v[14:15], v[38:39] op_sel_hi:[1,0]
	v_pk_mul_f32 v[16:17], v[16:17], v[38:39] op_sel_hi:[1,0]
	v_pk_mul_f32 v[10:11], v[10:11], v[38:39] op_sel_hi:[1,0]
	v_pk_mul_f32 v[12:13], v[12:13], v[38:39] op_sel_hi:[1,0]
	v_pk_mul_f32 v[6:7], v[6:7], v[38:39] op_sel_hi:[1,0]
	v_pk_mul_f32 v[8:9], v[8:9], v[38:39] op_sel_hi:[1,0]
	v_pk_mul_f32 v[2:3], v[2:3], v[38:39] op_sel_hi:[1,0]
	v_pk_mul_f32 v[4:5], v[4:5], v[38:39] op_sel_hi:[1,0]
	v_pk_mul_f32 v[20:21], v[32:33], v[16:17]
	v_pk_mul_f32 v[18:19], v[30:31], v[14:15]
	v_pk_mul_f32 v[24:25], v[28:29], v[12:13]
	v_pk_mul_f32 v[22:23], v[26:27], v[10:11]
	v_pk_mul_f32 v[36:37], v[48:49], v[8:9]
	v_pk_mul_f32 v[34:35], v[46:47], v[6:7]
	v_pk_mul_f32 v[40:41], v[44:45], v[4:5]
	v_pk_mul_f32 v[38:39], v[42:43], v[2:3]
	s_and_b64 vcc, exec, s[8:9]
	v_or_b32_e32 v4, s33, v191
	s_cbranch_vccnz .LBB0_375
	s_branch .LBB0_366
